# GEMM accumulators cleared with 64 v_mov_b64 instead of 127 v_mov_b32 per tile
# speedup vs baseline: 1.0150x; 1.0150x over previous
; template <class Epi, class Sched, bool ALIGN_EPI = false, bool SP2 = false, bool AROWS128 = false>
; __device__ __forceinline__ void gemm_phase(PG8_LAS unsigned char* lds, const Gemm g, const Sched& S, const Epi& E) {
;     ...
;         const bool has_next = S.next(ui + 1, nxt);
;         const char* nA = has_next ? (const char*)g.A + (size_t)nxt.pm * tstep : cA; const char* nB = has_next ? (const char*)g.Bt + (size_t)nxt.pn * tstep : cB;
;     ...
; #pragma unroll
;         for (int a = 0; a < 2; ++a)
; #pragma unroll
;             for (int b = 0; b < 2; ++b)
; #pragma unroll
;                 for (int m = 0; m < 4; ++m)
; #pragma unroll
;                     for (int n = 0; n < 2; ++n) acc[a][b][m][n] = (f32x4){0.f, 0.f, 0.f, 0.f};
;         cur = nxt; cA = nA; cB = nB; ++ui;
.LBB0_118:
	s_ashr_i32 s25, s24, 31
	s_lshl_b64 s[26:27], s[24:25], 19
	s_add_u32 s26, s46, s26
	s_addc_u32 s27, s47, s27
	s_and_b64 s[28:29], s[0:1], exec
	s_cselect_b32 s25, s27, s49
	s_cselect_b32 s76, s26, s48
	s_ashr_i32 s15, s14, 31
	s_lshl_b64 s[28:29], s[14:15], 19
	s_add_u32 s28, s82, s28
	s_addc_u32 s29, s83, s29
	s_and_b64 s[58:59], s[0:1], exec
	s_cselect_b32 s15, s29, s51
	s_cselect_b32 s77, s28, s50
	s_add_u32 s48, s48, 0x40080
	s_addc_u32 s49, s49, 0
	s_add_u32 s91, s50, 0x100
	v_mov_b32_e32 v0, 0
	s_addc_u32 s92, s51, 0
	s_mov_b32 s93, -2
	v_mov_b64_e32 v[0:1], 0
	v_mov_b64_e32 v[2:3], 0
	v_mov_b64_e32 v[4:5], 0
	v_mov_b64_e32 v[6:7], 0
	v_mov_b64_e32 v[8:9], 0
	v_mov_b64_e32 v[10:11], 0
	v_mov_b64_e32 v[12:13], 0
	v_mov_b64_e32 v[14:15], 0
	v_mov_b64_e32 v[16:17], 0
	v_mov_b64_e32 v[18:19], 0
	v_mov_b64_e32 v[20:21], 0
	v_mov_b64_e32 v[22:23], 0
	v_mov_b64_e32 v[24:25], 0
	v_mov_b64_e32 v[26:27], 0
	v_mov_b64_e32 v[28:29], 0
	v_mov_b64_e32 v[30:31], 0
	v_mov_b64_e32 v[32:33], 0
	v_mov_b64_e32 v[34:35], 0
	v_mov_b64_e32 v[36:37], 0
	v_mov_b64_e32 v[38:39], 0
	v_mov_b64_e32 v[40:41], 0
	v_mov_b64_e32 v[42:43], 0
	v_mov_b64_e32 v[44:45], 0
	v_mov_b64_e32 v[46:47], 0
	v_mov_b64_e32 v[48:49], 0
	v_mov_b64_e32 v[50:51], 0
	v_mov_b64_e32 v[52:53], 0
	v_mov_b64_e32 v[54:55], 0
	v_mov_b64_e32 v[56:57], 0
	v_mov_b64_e32 v[58:59], 0
	v_mov_b64_e32 v[60:61], 0
	v_mov_b64_e32 v[62:63], 0
	v_mov_b64_e32 v[64:65], 0
	v_mov_b64_e32 v[66:67], 0
	v_mov_b64_e32 v[68:69], 0
	v_mov_b64_e32 v[70:71], 0
	v_mov_b64_e32 v[72:73], 0
	v_mov_b64_e32 v[74:75], 0
	v_mov_b64_e32 v[76:77], 0
	v_mov_b64_e32 v[78:79], 0
	v_mov_b64_e32 v[80:81], 0
	v_mov_b64_e32 v[82:83], 0
	v_mov_b64_e32 v[84:85], 0
	v_mov_b64_e32 v[86:87], 0
	v_mov_b64_e32 v[88:89], 0
	v_mov_b64_e32 v[90:91], 0
	v_mov_b64_e32 v[92:93], 0
	v_mov_b64_e32 v[94:95], 0
	v_mov_b64_e32 v[96:97], 0
	v_mov_b64_e32 v[98:99], 0
	v_mov_b64_e32 v[100:101], 0
	v_mov_b64_e32 v[102:103], 0
	v_mov_b64_e32 v[104:105], 0
	v_mov_b64_e32 v[106:107], 0
	v_mov_b64_e32 v[108:109], 0
	v_mov_b64_e32 v[110:111], 0
	v_mov_b64_e32 v[112:113], 0
	v_mov_b64_e32 v[114:115], 0
	v_mov_b64_e32 v[116:117], 0
	v_mov_b64_e32 v[118:119], 0
	v_mov_b64_e32 v[120:121], 0
	v_mov_b64_e32 v[122:123], 0
	v_mov_b64_e32 v[124:125], 0
	v_mov_b64_e32 v[126:127], 0

; template <class Epi, class Sched, bool ALIGN_EPI = false, bool SP2 = false, bool AROWS128 = false>
; __device__ __forceinline__ void gemm_phase(PG8_LAS unsigned char* lds, const Gemm g, const Sched& S, const Epi& E) {
;     ...
;         const bool has_next = S.next(ui + 1, nxt);
;         const char* nA = has_next ? (const char*)g.A + (size_t)nxt.pm * tstep : cA; const char* nB = has_next ? (const char*)g.Bt + (size_t)nxt.pn * tstep : cB;
;     ...
; #pragma unroll
;         for (int a = 0; a < 2; ++a)
; #pragma unroll
;             for (int b = 0; b < 2; ++b)
; #pragma unroll
;                 for (int m = 0; m < 4; ++m)
; #pragma unroll
;                     for (int n = 0; n < 2; ++n) acc[a][b][m][n] = (f32x4){0.f, 0.f, 0.f, 0.f};
;         cur = nxt; cA = nA; cB = nB; ++ui;
.LBB0_488:
	s_ashr_i32 s15, s14, 31
	s_lshl_b64 s[16:17], s[14:15], 19
	s_add_u32 s16, s46, s16
	s_addc_u32 s17, s47, s17
	s_and_b64 s[18:19], s[0:1], exec
	s_cselect_b32 s15, s17, s27
	s_cselect_b32 s76, s16, s26
	s_ashr_i32 s13, s12, 31
	s_lshl_b64 s[18:19], s[12:13], 19
	s_add_u32 s18, s20, s18
	s_addc_u32 s19, s21, s19
	s_and_b64 s[30:31], s[0:1], exec
	s_cselect_b32 s13, s19, s29
	s_cselect_b32 s77, s18, s28
	s_add_u32 s26, s26, 0x40080
	s_addc_u32 s27, s27, 0
	s_add_u32 s82, s28, 0x100
	v_mov_b32_e32 v0, 0
	s_addc_u32 s83, s29, 0
	s_mov_b32 s84, -2
	v_mov_b64_e32 v[0:1], 0
	v_mov_b64_e32 v[2:3], 0
	v_mov_b64_e32 v[4:5], 0
	v_mov_b64_e32 v[6:7], 0
	v_mov_b64_e32 v[8:9], 0
	v_mov_b64_e32 v[10:11], 0
	v_mov_b64_e32 v[12:13], 0
	v_mov_b64_e32 v[14:15], 0
	v_mov_b64_e32 v[16:17], 0
	v_mov_b64_e32 v[18:19], 0
	v_mov_b64_e32 v[20:21], 0
	v_mov_b64_e32 v[22:23], 0
	v_mov_b64_e32 v[24:25], 0
	v_mov_b64_e32 v[26:27], 0
	v_mov_b64_e32 v[28:29], 0
	v_mov_b64_e32 v[30:31], 0
	v_mov_b64_e32 v[32:33], 0
	v_mov_b64_e32 v[34:35], 0
	v_mov_b64_e32 v[36:37], 0
	v_mov_b64_e32 v[38:39], 0
	v_mov_b64_e32 v[40:41], 0
	v_mov_b64_e32 v[42:43], 0
	v_mov_b64_e32 v[44:45], 0
	v_mov_b64_e32 v[46:47], 0
	v_mov_b64_e32 v[48:49], 0
	v_mov_b64_e32 v[50:51], 0
	v_mov_b64_e32 v[52:53], 0
	v_mov_b64_e32 v[54:55], 0
	v_mov_b64_e32 v[56:57], 0
	v_mov_b64_e32 v[58:59], 0
	v_mov_b64_e32 v[60:61], 0
	v_mov_b64_e32 v[62:63], 0
	v_mov_b64_e32 v[64:65], 0
	v_mov_b64_e32 v[66:67], 0
	v_mov_b64_e32 v[68:69], 0
	v_mov_b64_e32 v[70:71], 0
	v_mov_b64_e32 v[72:73], 0
	v_mov_b64_e32 v[74:75], 0
	v_mov_b64_e32 v[76:77], 0
	v_mov_b64_e32 v[78:79], 0
	v_mov_b64_e32 v[80:81], 0
	v_mov_b64_e32 v[82:83], 0
	v_mov_b64_e32 v[84:85], 0
	v_mov_b64_e32 v[86:87], 0
	v_mov_b64_e32 v[88:89], 0
	v_mov_b64_e32 v[90:91], 0
	v_mov_b64_e32 v[92:93], 0
	v_mov_b64_e32 v[94:95], 0
	v_mov_b64_e32 v[96:97], 0
	v_mov_b64_e32 v[98:99], 0
	v_mov_b64_e32 v[100:101], 0
	v_mov_b64_e32 v[102:103], 0
	v_mov_b64_e32 v[104:105], 0
	v_mov_b64_e32 v[106:107], 0
	v_mov_b64_e32 v[108:109], 0
	v_mov_b64_e32 v[110:111], 0
	v_mov_b64_e32 v[112:113], 0
	v_mov_b64_e32 v[114:115], 0
	v_mov_b64_e32 v[116:117], 0
	v_mov_b64_e32 v[118:119], 0
	v_mov_b64_e32 v[120:121], 0
	v_mov_b64_e32 v[122:123], 0
	v_mov_b64_e32 v[124:125], 0
	v_mov_b64_e32 v[126:127], 0

; template <class Epi, class Sched, bool ALIGN_EPI = false, bool SP2 = false, bool AROWS128 = false>
; __device__ __forceinline__ void gemm_phase(PG8_LAS unsigned char* lds, const Gemm g, const Sched& S, const Epi& E) {
;     ...
;         const bool has_next = S.next(ui + 1, nxt);
;         const char* nA = has_next ? (const char*)g.A + (size_t)nxt.pm * tstep : cA; const char* nB = has_next ? (const char*)g.Bt + (size_t)nxt.pn * tstep : cB;
;     ...
; #pragma unroll
;         for (int a = 0; a < 2; ++a)
; #pragma unroll
;             for (int b = 0; b < 2; ++b)
; #pragma unroll
;                 for (int m = 0; m < 4; ++m)
; #pragma unroll
;                     for (int n = 0; n < 2; ++n) acc[a][b][m][n] = (f32x4){0.f, 0.f, 0.f, 0.f};
;         cur = nxt; cA = nA; cB = nB; ++ui;
.LBB0_625:
	s_ashr_i32 s55, s54, 31
	s_lshl_b64 s[56:57], s[54:55], 19
	s_add_u32 s56, s46, s56
	s_addc_u32 s57, s47, s57
	s_and_b64 s[58:59], s[14:15], exec
	s_cselect_b32 s17, s57, s19
	s_cselect_b32 s33, s56, s18
	s_ashr_i32 s53, s52, 31
	s_lshl_b64 s[58:59], s[52:53], 19
	s_add_u32 s58, s78, s58
	s_addc_u32 s59, s79, s59
	s_and_b64 s[72:73], s[14:15], exec
	s_cselect_b32 s53, s59, s21
	s_cselect_b32 s55, s58, s20
	s_add_u32 s18, s18, 0x20080
	s_addc_u32 s19, s19, 0
	s_add_u32 s65, s20, 0x100
	v_mov_b32_e32 v0, 0
	s_addc_u32 s72, s21, 0
	s_mov_b32 s73, -2
	v_mov_b64_e32 v[0:1], 0
	v_mov_b64_e32 v[2:3], 0
	v_mov_b64_e32 v[4:5], 0
	v_mov_b64_e32 v[6:7], 0
	v_mov_b64_e32 v[8:9], 0
	v_mov_b64_e32 v[10:11], 0
	v_mov_b64_e32 v[12:13], 0
	v_mov_b64_e32 v[14:15], 0
	v_mov_b64_e32 v[16:17], 0
	v_mov_b64_e32 v[18:19], 0
	v_mov_b64_e32 v[20:21], 0
	v_mov_b64_e32 v[22:23], 0
	v_mov_b64_e32 v[24:25], 0
	v_mov_b64_e32 v[26:27], 0
	v_mov_b64_e32 v[28:29], 0
	v_mov_b64_e32 v[30:31], 0
	v_mov_b64_e32 v[32:33], 0
	v_mov_b64_e32 v[34:35], 0
	v_mov_b64_e32 v[36:37], 0
	v_mov_b64_e32 v[38:39], 0
	v_mov_b64_e32 v[40:41], 0
	v_mov_b64_e32 v[42:43], 0
	v_mov_b64_e32 v[44:45], 0
	v_mov_b64_e32 v[46:47], 0
	v_mov_b64_e32 v[48:49], 0
	v_mov_b64_e32 v[50:51], 0
	v_mov_b64_e32 v[52:53], 0
	v_mov_b64_e32 v[54:55], 0
	v_mov_b64_e32 v[56:57], 0
	v_mov_b64_e32 v[58:59], 0
	v_mov_b64_e32 v[60:61], 0
	v_mov_b64_e32 v[62:63], 0
	v_mov_b64_e32 v[64:65], 0
	v_mov_b64_e32 v[66:67], 0
	v_mov_b64_e32 v[68:69], 0
	v_mov_b64_e32 v[70:71], 0
	v_mov_b64_e32 v[104:105], 0
	v_mov_b64_e32 v[106:107], 0
	v_mov_b64_e32 v[108:109], 0
	v_mov_b64_e32 v[110:111], 0
	v_mov_b64_e32 v[112:113], 0
	v_mov_b64_e32 v[114:115], 0
	v_mov_b64_e32 v[116:117], 0
	v_mov_b64_e32 v[118:119], 0
	v_mov_b64_e32 v[120:121], 0
	v_mov_b64_e32 v[122:123], 0
	v_mov_b64_e32 v[124:125], 0
	v_mov_b64_e32 v[126:127], 0
	v_mov_b64_e32 v[128:129], 0
	v_mov_b64_e32 v[130:131], 0
	v_mov_b64_e32 v[132:133], 0
	v_mov_b64_e32 v[134:135], 0
	v_mov_b64_e32 v[136:137], 0
	v_mov_b64_e32 v[138:139], 0
	v_mov_b64_e32 v[140:141], 0
	v_mov_b64_e32 v[142:143], 0
	v_mov_b64_e32 v[144:145], 0
	v_mov_b64_e32 v[146:147], 0
	v_mov_b64_e32 v[148:149], 0
	v_mov_b64_e32 v[150:151], 0
	v_mov_b64_e32 v[152:153], 0
	v_mov_b64_e32 v[154:155], 0
	v_mov_b64_e32 v[156:157], 0
	v_mov_b64_e32 v[158:159], 0

; template <class Epi, class Sched, bool ALIGN_EPI = false, bool SP2 = false, bool AROWS128 = false>
; __device__ __forceinline__ void gemm_phase(PG8_LAS unsigned char* lds, const Gemm g, const Sched& S, const Epi& E) {
;     ...
;         const bool has_next = S.next(ui + 1, nxt);
;         const char* nA = has_next ? (const char*)g.A + (size_t)nxt.pm * tstep : cA; const char* nB = has_next ? (const char*)g.Bt + (size_t)nxt.pn * tstep : cB;
;     ...
; #pragma unroll
;         for (int a = 0; a < 2; ++a)
; #pragma unroll
;             for (int b = 0; b < 2; ++b)
; #pragma unroll
;                 for (int m = 0; m < 4; ++m)
; #pragma unroll
;                     for (int n = 0; n < 2; ++n) acc[a][b][m][n] = (f32x4){0.f, 0.f, 0.f, 0.f};
;         cur = nxt; cA = nA; cB = nB; ++ui;
.LBB0_751:
	s_ashr_i32 s25, s24, 31
	s_lshl_b64 s[26:27], s[24:25], 21
	s_add_u32 s26, s44, s26
	s_addc_u32 s27, s45, s27
	s_and_b64 s[28:29], s[0:1], exec
	s_cselect_b32 s25, s27, s37
	s_cselect_b32 s65, s26, s36
	s_ashr_i32 s21, s20, 31
	s_lshl_b64 s[28:29], s[20:21], 21
	v_readlane_b32 s48, v255, 13
	v_readlane_b32 s49, v255, 14
	s_add_u32 s28, s48, s28
	s_addc_u32 s29, s49, s29
	s_and_b64 s[48:49], s[0:1], exec
	s_cselect_b32 s21, s29, s39
	s_cselect_b32 s72, s28, s38
	s_add_u32 s36, s36, 0x100080
	s_addc_u32 s37, s37, 0
	s_add_u32 s73, s38, 0x100
	v_mov_b32_e32 v0, 0
	s_addc_u32 s76, s39, 0
	s_mov_b32 s77, -2
	v_mov_b64_e32 v[0:1], 0
	v_mov_b64_e32 v[2:3], 0
	v_mov_b64_e32 v[4:5], 0
	v_mov_b64_e32 v[6:7], 0
	v_mov_b64_e32 v[8:9], 0
	v_mov_b64_e32 v[10:11], 0
	v_mov_b64_e32 v[12:13], 0
	v_mov_b64_e32 v[14:15], 0
	v_mov_b64_e32 v[16:17], 0
	v_mov_b64_e32 v[18:19], 0
	v_mov_b64_e32 v[20:21], 0
	v_mov_b64_e32 v[22:23], 0
	v_mov_b64_e32 v[24:25], 0
	v_mov_b64_e32 v[26:27], 0
	v_mov_b64_e32 v[28:29], 0
	v_mov_b64_e32 v[30:31], 0
	v_mov_b64_e32 v[32:33], 0
	v_mov_b64_e32 v[34:35], 0
	v_mov_b64_e32 v[36:37], 0
	v_mov_b64_e32 v[38:39], 0
	v_mov_b64_e32 v[40:41], 0
	v_mov_b64_e32 v[42:43], 0
	v_mov_b64_e32 v[44:45], 0
	v_mov_b64_e32 v[46:47], 0
	v_mov_b64_e32 v[48:49], 0
	v_mov_b64_e32 v[50:51], 0
	v_mov_b64_e32 v[52:53], 0
	v_mov_b64_e32 v[54:55], 0
	v_mov_b64_e32 v[56:57], 0
	v_mov_b64_e32 v[58:59], 0
	v_mov_b64_e32 v[60:61], 0
	v_mov_b64_e32 v[62:63], 0
	v_mov_b64_e32 v[64:65], 0
	v_mov_b64_e32 v[66:67], 0
	v_mov_b64_e32 v[68:69], 0
	v_mov_b64_e32 v[70:71], 0
	v_mov_b64_e32 v[72:73], 0
	v_mov_b64_e32 v[74:75], 0
	v_mov_b64_e32 v[76:77], 0
	v_mov_b64_e32 v[78:79], 0
	v_mov_b64_e32 v[80:81], 0
	v_mov_b64_e32 v[82:83], 0
	v_mov_b64_e32 v[84:85], 0
	v_mov_b64_e32 v[86:87], 0
	v_mov_b64_e32 v[88:89], 0
	v_mov_b64_e32 v[90:91], 0
	v_mov_b64_e32 v[92:93], 0
	v_mov_b64_e32 v[94:95], 0
	v_mov_b64_e32 v[96:97], 0
	v_mov_b64_e32 v[98:99], 0
	v_mov_b64_e32 v[100:101], 0
	v_mov_b64_e32 v[102:103], 0
	v_mov_b64_e32 v[104:105], 0
	v_mov_b64_e32 v[106:107], 0
	v_mov_b64_e32 v[108:109], 0
	v_mov_b64_e32 v[110:111], 0
	v_mov_b64_e32 v[112:113], 0
	v_mov_b64_e32 v[114:115], 0
	v_mov_b64_e32 v[116:117], 0
	v_mov_b64_e32 v[118:119], 0
	v_mov_b64_e32 v[120:121], 0
	v_mov_b64_e32 v[122:123], 0
	v_mov_b64_e32 v[124:125], 0
	v_mov_b64_e32 v[126:127], 0

; template <class Epi, class Sched, bool ALIGN_EPI = false, bool SP2 = false, bool AROWS128 = false>
; __device__ __forceinline__ void gemm_phase(PG8_LAS unsigned char* lds, const Gemm g, const Sched& S, const Epi& E) {
;     ...
;         const bool has_next = S.next(ui + 1, nxt);
;         const char* nA = has_next ? (const char*)g.A + (size_t)nxt.pm * tstep : cA; const char* nB = has_next ? (const char*)g.Bt + (size_t)nxt.pn * tstep : cB;
;     ...
; #pragma unroll
;         for (int a = 0; a < 2; ++a)
; #pragma unroll
;             for (int b = 0; b < 2; ++b)
; #pragma unroll
;                 for (int m = 0; m < 4; ++m)
; #pragma unroll
;                     for (int n = 0; n < 2; ++n) acc[a][b][m][n] = (f32x4){0.f, 0.f, 0.f, 0.f};
;         cur = nxt; cA = nA; cB = nB; ++ui;
.LBB0_885:
	s_ashr_i32 s31, s30, 31
	s_lshl_b64 s[36:37], s[30:31], 19
	s_add_u32 s36, s44, s36
	s_addc_u32 s37, s45, s37
	s_and_b64 s[38:39], s[0:1], exec
	s_cselect_b32 s31, s37, s43
	s_cselect_b32 s65, s36, s42
	s_ashr_i32 s29, s28, 31
	s_lshl_b64 s[38:39], s[28:29], 19
	s_add_u32 s38, s8, s38
	s_addc_u32 s39, s9, s39
	s_and_b64 s[48:49], s[0:1], exec
	s_cselect_b32 s29, s39, s47
	s_cselect_b32 s66, s38, s46
	s_add_u32 s42, s42, 0x40080
	s_addc_u32 s43, s43, 0
	s_add_u32 s67, s46, 0x100
	v_mov_b32_e32 v0, 0
	s_addc_u32 s72, s47, 0
	s_mov_b32 s73, -2
	v_mov_b64_e32 v[0:1], 0
	v_mov_b64_e32 v[2:3], 0
	v_mov_b64_e32 v[4:5], 0
	v_mov_b64_e32 v[6:7], 0
	v_mov_b64_e32 v[8:9], 0
	v_mov_b64_e32 v[10:11], 0
	v_mov_b64_e32 v[12:13], 0
	v_mov_b64_e32 v[14:15], 0
	v_mov_b64_e32 v[16:17], 0
	v_mov_b64_e32 v[18:19], 0
	v_mov_b64_e32 v[20:21], 0
	v_mov_b64_e32 v[22:23], 0
	v_mov_b64_e32 v[24:25], 0
	v_mov_b64_e32 v[26:27], 0
	v_mov_b64_e32 v[28:29], 0
	v_mov_b64_e32 v[30:31], 0
	v_mov_b64_e32 v[32:33], 0
	v_mov_b64_e32 v[34:35], 0
	v_mov_b64_e32 v[36:37], 0
	v_mov_b64_e32 v[38:39], 0
	v_mov_b64_e32 v[40:41], 0
	v_mov_b64_e32 v[42:43], 0
	v_mov_b64_e32 v[44:45], 0
	v_mov_b64_e32 v[46:47], 0
	v_mov_b64_e32 v[48:49], 0
	v_mov_b64_e32 v[50:51], 0
	v_mov_b64_e32 v[52:53], 0
	v_mov_b64_e32 v[54:55], 0
	v_mov_b64_e32 v[56:57], 0
	v_mov_b64_e32 v[58:59], 0
	v_mov_b64_e32 v[60:61], 0
	v_mov_b64_e32 v[62:63], 0
	v_mov_b64_e32 v[64:65], 0
	v_mov_b64_e32 v[66:67], 0
	v_mov_b64_e32 v[68:69], 0
	v_mov_b64_e32 v[70:71], 0
	v_mov_b64_e32 v[72:73], 0
	v_mov_b64_e32 v[74:75], 0
	v_mov_b64_e32 v[76:77], 0
	v_mov_b64_e32 v[78:79], 0
	v_mov_b64_e32 v[80:81], 0
	v_mov_b64_e32 v[82:83], 0
	v_mov_b64_e32 v[84:85], 0
	v_mov_b64_e32 v[86:87], 0
	v_mov_b64_e32 v[88:89], 0
	v_mov_b64_e32 v[90:91], 0
	v_mov_b64_e32 v[92:93], 0
	v_mov_b64_e32 v[94:95], 0
	v_mov_b64_e32 v[96:97], 0
	v_mov_b64_e32 v[98:99], 0
	v_mov_b64_e32 v[100:101], 0
	v_mov_b64_e32 v[102:103], 0
	v_mov_b64_e32 v[104:105], 0
	v_mov_b64_e32 v[106:107], 0
	v_mov_b64_e32 v[108:109], 0
	v_mov_b64_e32 v[110:111], 0
	v_mov_b64_e32 v[112:113], 0
	v_mov_b64_e32 v[114:115], 0
	v_mov_b64_e32 v[116:117], 0
	v_mov_b64_e32 v[118:119], 0
	v_mov_b64_e32 v[120:121], 0
	v_mov_b64_e32 v[122:123], 0
	v_mov_b64_e32 v[124:125], 0
	v_mov_b64_e32 v[126:127], 0

; template <class Epi, class Sched, bool ALIGN_EPI = false, bool SP2 = false, bool AROWS128 = false>
; __device__ __forceinline__ void gemm_phase(PG8_LAS unsigned char* lds, const Gemm g, const Sched& S, const Epi& E) {
;     ...
;         const bool has_next = S.next(ui + 1, nxt);
;         const char* nA = has_next ? (const char*)g.A + (size_t)nxt.pm * tstep : cA; const char* nB = has_next ? (const char*)g.Bt + (size_t)nxt.pn * tstep : cB;
;     ...
; #pragma unroll
;         for (int a = 0; a < 2; ++a)
; #pragma unroll
;             for (int b = 0; b < 2; ++b)
; #pragma unroll
;                 for (int m = 0; m < 4; ++m)
; #pragma unroll
;                     for (int n = 0; n < 2; ++n) acc[a][b][m][n] = (f32x4){0.f, 0.f, 0.f, 0.f};
;         cur = nxt; cA = nA; cB = nB; ++ui;
.LBB0_901:
	s_ashr_i32 s27, s26, 31
	s_lshl_b64 s[28:29], s[26:27], 17
	s_add_u32 s28, s33, s28
	s_addc_u32 s29, s35, s29
	s_and_b64 s[30:31], s[0:1], exec
	s_cselect_b32 s27, s29, s41
	s_cselect_b32 s79, s28, s40
	s_ashr_i32 s25, s24, 31
	s_lshl_b64 s[30:31], s[24:25], 17
	s_add_u32 s30, s6, s30
	s_addc_u32 s31, s7, s31
	s_and_b64 s[42:43], s[0:1], exec
	v_mov_b32_e32 v0, 0
	s_cselect_b32 s25, s31, s39
	s_cselect_b32 s80, s30, s38
	s_mov_b32 s46, 0
	s_mov_b64 s[42:43], -1
	s_mov_b64 s[44:45], 0
	v_mov_b64_e32 v[0:1], 0
	v_mov_b64_e32 v[2:3], 0
	v_mov_b64_e32 v[4:5], 0
	v_mov_b64_e32 v[6:7], 0
	v_mov_b64_e32 v[8:9], 0
	v_mov_b64_e32 v[10:11], 0
	v_mov_b64_e32 v[12:13], 0
	v_mov_b64_e32 v[14:15], 0
	v_mov_b64_e32 v[16:17], 0
	v_mov_b64_e32 v[18:19], 0
	v_mov_b64_e32 v[20:21], 0
	v_mov_b64_e32 v[22:23], 0
	v_mov_b64_e32 v[24:25], 0
	v_mov_b64_e32 v[26:27], 0
	v_mov_b64_e32 v[28:29], 0
	v_mov_b64_e32 v[30:31], 0
	v_mov_b64_e32 v[32:33], 0
	v_mov_b64_e32 v[34:35], 0
	v_mov_b64_e32 v[36:37], 0
	v_mov_b64_e32 v[38:39], 0
	v_mov_b64_e32 v[40:41], 0
	v_mov_b64_e32 v[42:43], 0
	v_mov_b64_e32 v[44:45], 0
	v_mov_b64_e32 v[46:47], 0
	v_mov_b64_e32 v[48:49], 0
	v_mov_b64_e32 v[50:51], 0
	v_mov_b64_e32 v[52:53], 0
	v_mov_b64_e32 v[54:55], 0
	v_mov_b64_e32 v[56:57], 0
	v_mov_b64_e32 v[58:59], 0
	v_mov_b64_e32 v[60:61], 0
	v_mov_b64_e32 v[62:63], 0
	v_mov_b64_e32 v[64:65], 0
	v_mov_b64_e32 v[66:67], 0
	v_mov_b64_e32 v[68:69], 0
	v_mov_b64_e32 v[70:71], 0
	v_mov_b64_e32 v[72:73], 0
	v_mov_b64_e32 v[74:75], 0
	v_mov_b64_e32 v[76:77], 0
	v_mov_b64_e32 v[78:79], 0
	v_mov_b64_e32 v[80:81], 0
	v_mov_b64_e32 v[82:83], 0
	v_mov_b64_e32 v[84:85], 0
	v_mov_b64_e32 v[86:87], 0
	v_mov_b64_e32 v[88:89], 0
	v_mov_b64_e32 v[90:91], 0
	v_mov_b64_e32 v[92:93], 0
	v_mov_b64_e32 v[94:95], 0
	v_mov_b64_e32 v[96:97], 0
	v_mov_b64_e32 v[98:99], 0
	v_mov_b64_e32 v[100:101], 0
	v_mov_b64_e32 v[102:103], 0
	v_mov_b64_e32 v[104:105], 0
	v_mov_b64_e32 v[106:107], 0
	v_mov_b64_e32 v[108:109], 0
	v_mov_b64_e32 v[110:111], 0
	v_mov_b64_e32 v[112:113], 0
	v_mov_b64_e32 v[114:115], 0
	v_mov_b64_e32 v[116:117], 0
	v_mov_b64_e32 v[118:119], 0
	v_mov_b64_e32 v[120:121], 0
	v_mov_b64_e32 v[122:123], 0
	v_mov_b64_e32 v[124:125], 0
	v_mov_b64_e32 v[126:127], 0
